# DA fast path prio: A-wave QK cluster raised to prio 2 (above B-wave MFMA prio 1)
# baseline (speedup 1.0000x reference)
; template <int NC, int DQK, int DV, bool CAUSAL, bool PF> ...
;     ...
;     _Pragma("unroll") for (int c = 0; c < NC; ++c) {
;       f32x4 s[4];
;       _Pragma("unroll") for (int m = 0; m < 4; ++m) s[m] = f32x4{0.f, 0.f, 0.f, 0.f};
;       _Pragma("unroll") for (int ks = 0; ks < NKS; ++ks) _Pragma("unroll") for (int m = 0; m < 4; ++m) {
;         bf16x8 a = *(const bf16x8*)&Kb[(16 * m + fr) * KLD + c * DQK + ks * 32 + fq * 8];
;         s[m] = __builtin_amdgcn_mfma_f32_16x16x32_bf16(a, qf[c][ks], s[m], 0, 0, 0);
;       }
;       constexpr float THR = 8.f;
;       float tnew, psum = 0.f;
;       if (general) {
;         float tmax = -1e30f;
;         _Pragma("unroll") for (int m = 0; m < 4; ++m) _Pragma("unroll") for (int j = 0; j < 4; ++j) {
;           float v = s[m][j] * scale_log2 + bv[m][j];
;           s[m][j] = v; tmax = fmaxf(tmax, v);
;         }
;         tnew = tmax;
;       } else {
;         float rmax = fmaxf(fmaxf(s[0][0], s[0][1]), fmaxf(s[0][2], s[0][3]));
;         _Pragma("unroll") for (int m = 1; m < 4; ++m) rmax = fmaxf(rmax, fmaxf(fmaxf(s[m][0], s[m][1]), fmaxf(s[m][2], s[m][3])));
;         tnew = rmax * scale_log2 + bb;
;       }
;       if (__builtin_amdgcn_ballot_w64(tnew - mrun[c] > THR) != 0ull) {
.Lda_fast:
	s_setprio 2
	v_add3_u32 v172, s38, v32, v195
	v_add3_u32 v173, s37, v32, v193
	ds_read_b128 v[146:149], v172
	ds_read_b128 v[150:153], v172 offset:4608
	ds_read_b128 v[154:157], v172 offset:9216
	ds_read_b128 v[158:161], v172 offset:13824
	ds_read_b128 v[16:19], v172 offset:64
	ds_read_b128 v[20:23], v172 offset:4672
	ds_read_b128 v[24:27], v172 offset:9280
	ds_read_b128 v[28:31], v172 offset:13888
	ds_read_b128 v[0:3], v172 offset:128
	ds_read_b128 v[4:7], v172 offset:4736
	ds_read_b128 v[8:11], v172 offset:9344
	ds_read_b128 v[12:15], v172 offset:13952
	s_waitcnt lgkmcnt(10)
	v_mfma_f32_16x16x32_bf16 v[146:149], v[146:149], v[138:141], 0
	v_mfma_f32_16x16x32_bf16 v[150:153], v[150:153], v[138:141], 0
	s_waitcnt lgkmcnt(8)
	v_mfma_f32_16x16x32_bf16 v[154:157], v[154:157], v[138:141], 0
	v_mfma_f32_16x16x32_bf16 v[158:161], v[158:161], v[138:141], 0
	s_waitcnt lgkmcnt(4)
	v_mfma_f32_16x16x32_bf16 v[146:149], v[16:19], v[134:137], v[146:149]
	v_mfma_f32_16x16x32_bf16 v[150:153], v[20:23], v[134:137], v[150:153]
	v_mfma_f32_16x16x32_bf16 v[154:157], v[24:27], v[134:137], v[154:157]
	v_mfma_f32_16x16x32_bf16 v[158:161], v[28:31], v[134:137], v[158:161]
	ds_read_b128 v[16:19], v172 offset:192
	ds_read_b128 v[20:23], v172 offset:4800
	ds_read_b128 v[24:27], v172 offset:9408
	ds_read_b128 v[28:31], v172 offset:14016
	ds_read_b128 v[122:125], v173 offset:36864
	ds_read_b128 v[126:129], v173 offset:39424
	ds_read_b128 v[130:133], v173 offset:41984
	ds_read_b128 v[142:145], v173 offset:44544
	s_waitcnt lgkmcnt(8)
	v_mfma_f32_16x16x32_bf16 v[0:3], v[0:3], v[118:121], 0
	v_mfma_f32_16x16x32_bf16 v[4:7], v[4:7], v[118:121], 0
	v_mfma_f32_16x16x32_bf16 v[8:11], v[8:11], v[118:121], 0
	v_mfma_f32_16x16x32_bf16 v[12:15], v[12:15], v[118:121], 0
	s_setprio 0
	v_max3_f32 v174, v146, v147, v148
	v_max3_f32 v175, v149, v150, v151
	v_max3_f32 v174, v174, v152, v153
	v_max3_f32 v175, v175, v154, v155
	v_max3_f32 v174, v174, v156, v157
	v_max3_f32 v175, v175, v158, v159
	v_max3_f32 v174, v174, v160, v161
	v_max_f32_e32 v174, v174, v175
	v_fmamk_f32 v174, v174, 0x3e38aa3b, v170
	v_sub_f32_e32 v175, v174, v194
	v_cmp_lt_f32_e32 vcc, s33, v175
	s_cbranch_vccnz .Lda_resc0
